# weight-transpose read-out (ff1 stagger prefix + w_in deferred prep): 16 serial ds_read2_b32+wait pairs issued up front with counted lgkmcnt
# speedup vs baseline: 1.0024x; 1.0024x over previous
.LBB0_417:
	s_ashr_i32 s85, s84, 31
	s_lshl_b64 s[10:11], s[84:85], 1
	s_add_u32 s10, s78, s10
	s_addc_u32 s11, s79, s11
	v_mov_b32_e32 v33, v175
	v_lshl_add_u64 v[34:35], s[10:11], 0, v[32:33]
	ds_read2_b32 v[130:131], v45 offset1:129
	v_add_u32_e32 v33, 0x400, v45
	ds_read2_b32 v[132:133], v33 offset0:2 offset1:131
	v_add_u32_e32 v33, 0x800, v45
	ds_read2_b32 v[134:135], v33 offset0:4 offset1:133
	v_add_u32_e32 v33, 0xc00, v45
	ds_read2_b32 v[136:137], v33 offset0:6 offset1:135
	ds_read2_b32 v[138:139], v47 offset1:129
	v_add_u32_e32 v33, 0x400, v47
	ds_read2_b32 v[140:141], v33 offset0:2 offset1:131
	v_add_u32_e32 v33, 0x800, v47
	ds_read2_b32 v[142:143], v33 offset0:4 offset1:133
	v_add_u32_e32 v33, 0xc00, v47
	ds_read2_b32 v[144:145], v33 offset0:6 offset1:135
	ds_read2_b32 v[146:147], v49 offset1:129
	v_add_u32_e32 v33, 0x400, v49
	ds_read2_b32 v[148:149], v33 offset0:2 offset1:131
	v_add_u32_e32 v33, 0x800, v49
	ds_read2_b32 v[150:151], v33 offset0:4 offset1:133
	v_add_u32_e32 v33, 0xc00, v49
	ds_read2_b32 v[152:153], v33 offset0:6 offset1:135
	ds_read2_b32 v[154:155], v51 offset1:129
	v_add_u32_e32 v33, 0x400, v51
	ds_read2_b32 v[156:157], v33 offset0:2 offset1:131
	v_add_u32_e32 v33, 0x800, v51
	ds_read2_b32 v[158:159], v33 offset0:4 offset1:133
	v_add_u32_e32 v33, 0xc00, v51
	ds_read2_b32 v[160:161], v33 offset0:6 offset1:135
	s_waitcnt lgkmcnt(12)
	v_cvt_pk_bf16_f32 v130, v130, v131
	v_cvt_pk_bf16_f32 v131, v132, v133
	v_cvt_pk_bf16_f32 v132, v134, v135
	v_cvt_pk_bf16_f32 v133, v136, v137
	v_add_u32_e32 v33, s90, v44
	v_ashrrev_i32_e32 v64, 31, v33
	v_mul_lo_u32 v66, s76, v64
	v_mul_lo_u32 v67, s77, v33
	v_mad_u64_u32 v[64:65], s[10:11], s76, v33, 0
	v_add3_u32 v65, v65, v66, v67
	v_lshl_add_u64 v[64:65], v[64:65], 1, v[34:35]
	global_store_dwordx4 v[64:65], v[130:133], off
	s_waitcnt lgkmcnt(8)
	v_cvt_pk_bf16_f32 v138, v138, v139
	v_cvt_pk_bf16_f32 v139, v140, v141
	v_cvt_pk_bf16_f32 v140, v142, v143
	v_cvt_pk_bf16_f32 v141, v144, v145
	v_add_u32_e32 v33, s90, v46
	v_ashrrev_i32_e32 v64, 31, v33
	v_mul_lo_u32 v66, s76, v64
	v_mul_lo_u32 v67, s77, v33
	v_mad_u64_u32 v[64:65], s[10:11], s76, v33, 0
	v_add3_u32 v65, v65, v66, v67
	v_lshl_add_u64 v[64:65], v[64:65], 1, v[34:35]
	global_store_dwordx4 v[64:65], v[138:141], off
	s_waitcnt lgkmcnt(4)
	v_cvt_pk_bf16_f32 v146, v146, v147
	v_cvt_pk_bf16_f32 v147, v148, v149
	v_cvt_pk_bf16_f32 v148, v150, v151
	v_cvt_pk_bf16_f32 v149, v152, v153
	v_add_u32_e32 v33, s90, v48
	v_ashrrev_i32_e32 v64, 31, v33
	v_mul_lo_u32 v66, s76, v64
	v_mul_lo_u32 v67, s77, v33
	v_mad_u64_u32 v[64:65], s[10:11], s76, v33, 0
	v_add3_u32 v65, v65, v66, v67
	v_lshl_add_u64 v[64:65], v[64:65], 1, v[34:35]
	global_store_dwordx4 v[64:65], v[146:149], off
	s_waitcnt lgkmcnt(0)
	v_cvt_pk_bf16_f32 v154, v154, v155
	v_cvt_pk_bf16_f32 v155, v156, v157
	v_cvt_pk_bf16_f32 v156, v158, v159
	v_cvt_pk_bf16_f32 v157, v160, v161
	v_add_u32_e32 v33, s90, v50
	v_ashrrev_i32_e32 v64, 31, v33
	v_mul_lo_u32 v66, s76, v64
	v_mul_lo_u32 v67, s77, v33
	v_mad_u64_u32 v[64:65], s[10:11], s76, v33, 0
	v_add3_u32 v65, v65, v66, v67
	v_lshl_add_u64 v[34:35], v[64:65], 1, v[34:35]
	s_add_i32 s94, s94, s4
	s_add_i32 s21, s21, s20
	s_andn2_b64 vcc, exec, s[80:81]
	s_movk_i32 s80, 0x3fff
	s_movk_i32 s85, 0xf7f
	global_store_dwordx4 v[34:35], v[154:157], off
	s_barrier
	s_cbranch_vccz .LBB0_467

.LBB0_1200:
	s_ashr_i32 s79, s78, 31
	s_lshl_b64 s[12:13], s[78:79], 1
	s_add_u32 s12, s62, s12
	s_addc_u32 s13, s63, s13
	v_mov_b32_e32 v33, v175
	v_lshl_add_u64 v[34:35], s[12:13], 0, v[32:33]
	ds_read2_b32 v[130:131], v45 offset1:129
	v_add_u32_e32 v33, 0x400, v45
	ds_read2_b32 v[132:133], v33 offset0:2 offset1:131
	v_add_u32_e32 v33, 0x800, v45
	ds_read2_b32 v[134:135], v33 offset0:4 offset1:133
	v_add_u32_e32 v33, 0xc00, v45
	ds_read2_b32 v[136:137], v33 offset0:6 offset1:135
	ds_read2_b32 v[138:139], v47 offset1:129
	v_add_u32_e32 v33, 0x400, v47
	ds_read2_b32 v[140:141], v33 offset0:2 offset1:131
	v_add_u32_e32 v33, 0x800, v47
	ds_read2_b32 v[142:143], v33 offset0:4 offset1:133
	v_add_u32_e32 v33, 0xc00, v47
	ds_read2_b32 v[144:145], v33 offset0:6 offset1:135
	ds_read2_b32 v[146:147], v49 offset1:129
	v_add_u32_e32 v33, 0x400, v49
	ds_read2_b32 v[148:149], v33 offset0:2 offset1:131
	v_add_u32_e32 v33, 0x800, v49
	ds_read2_b32 v[150:151], v33 offset0:4 offset1:133
	v_add_u32_e32 v33, 0xc00, v49
	ds_read2_b32 v[152:153], v33 offset0:6 offset1:135
	ds_read2_b32 v[154:155], v51 offset1:129
	v_add_u32_e32 v33, 0x400, v51
	ds_read2_b32 v[156:157], v33 offset0:2 offset1:131
	v_add_u32_e32 v33, 0x800, v51
	ds_read2_b32 v[158:159], v33 offset0:4 offset1:133
	v_add_u32_e32 v33, 0xc00, v51
	ds_read2_b32 v[160:161], v33 offset0:6 offset1:135
	s_waitcnt lgkmcnt(12)
	v_cvt_pk_bf16_f32 v130, v130, v131
	v_cvt_pk_bf16_f32 v131, v132, v133
	v_cvt_pk_bf16_f32 v132, v134, v135
	v_cvt_pk_bf16_f32 v133, v136, v137
	v_add_u32_e32 v33, s26, v44
	v_ashrrev_i32_e32 v64, 31, v33
	v_mul_lo_u32 v66, s92, v64
	v_mul_lo_u32 v67, s93, v33
	v_mad_u64_u32 v[64:65], s[12:13], s92, v33, 0
	v_add3_u32 v65, v65, v66, v67
	v_lshl_add_u64 v[64:65], v[64:65], 1, v[34:35]
	global_store_dwordx4 v[64:65], v[130:133], off
	s_waitcnt lgkmcnt(8)
	v_cvt_pk_bf16_f32 v138, v138, v139
	v_cvt_pk_bf16_f32 v139, v140, v141
	v_cvt_pk_bf16_f32 v140, v142, v143
	v_cvt_pk_bf16_f32 v141, v144, v145
	v_add_u32_e32 v33, s26, v46
	v_ashrrev_i32_e32 v64, 31, v33
	v_mul_lo_u32 v66, s92, v64
	v_mul_lo_u32 v67, s93, v33
	v_mad_u64_u32 v[64:65], s[12:13], s92, v33, 0
	v_add3_u32 v65, v65, v66, v67
	v_lshl_add_u64 v[64:65], v[64:65], 1, v[34:35]
	global_store_dwordx4 v[64:65], v[138:141], off
	s_waitcnt lgkmcnt(4)
	v_cvt_pk_bf16_f32 v146, v146, v147
	v_cvt_pk_bf16_f32 v147, v148, v149
	v_cvt_pk_bf16_f32 v148, v150, v151
	v_cvt_pk_bf16_f32 v149, v152, v153
	v_add_u32_e32 v33, s26, v48
	v_ashrrev_i32_e32 v64, 31, v33
	v_mul_lo_u32 v66, s92, v64
	v_mul_lo_u32 v67, s93, v33
	v_mad_u64_u32 v[64:65], s[12:13], s92, v33, 0
	v_add3_u32 v65, v65, v66, v67
	v_lshl_add_u64 v[64:65], v[64:65], 1, v[34:35]
	global_store_dwordx4 v[64:65], v[146:149], off
	s_waitcnt lgkmcnt(0)
	v_cvt_pk_bf16_f32 v154, v154, v155
	v_cvt_pk_bf16_f32 v155, v156, v157
	v_cvt_pk_bf16_f32 v156, v158, v159
	v_cvt_pk_bf16_f32 v157, v160, v161
	v_add_u32_e32 v33, s26, v50
	v_ashrrev_i32_e32 v64, 31, v33
	v_mul_lo_u32 v66, s92, v64
	v_mul_lo_u32 v67, s93, v33
	v_mad_u64_u32 v[64:65], s[12:13], s92, v33, 0
	v_add3_u32 v65, v65, v66, v67
	v_lshl_add_u64 v[34:35], v[64:65], 1, v[34:35]
	s_add_i32 s24, s24, s4
	s_add_i32 s80, s80, s81
	s_andn2_b64 vcc, exec, s[94:95]
	global_store_dwordx4 v[34:35], v[154:157], off
	s_barrier
	s_cbranch_vccz .LBB0_1250
